# attention->out-proj grid sync made XCD-local: attention items remapped so XCD x computes batches 2x,2x+1; ctx out-proj tiles wait on arrival counter E
# speedup vs baseline: 1.0152x; 1.0007x over previous
; #define GLOBAL_PTR(T, p) ((T*)(__attribute__((address_space(1))) T*)(launder_u64((unsigned long long)(p))))
; DI const float* in_ptr(const Args& AR, int i) { asm volatile("" : "+s"(i)); return GLOBAL_PTR(const float, AR.in[i]); }
; #define GRID_SYNC() do { nbar += (unsigned)gridDim.x; grid_barrier(barw, nbar); } while (0)
; __global__ void __launch_bounds__(512, 2) fwd_megakernel(Args args) {
;     ...
;     unsigned* barw = GLOBAL_PTR(unsigned, args.ws); unsigned nbar = 0u;
;     grid.sync();
;     if (PM & 1) prologue_a(F, AR, 5, 6);
;     GRID_SYNC();
;     if (PM & 2) prologue_b(F, AR);
;     GRID_SYNC();
; #pragma unroll 1
;     for (int k_ = 0; k_ < 2; ++k_) {
;         if ((k_ == 0) == ((blockIdx.x & 1) != 0)) norm_phase(F, in_ptr(AR, 0), in_ptr(AR, 2), in_ptr(AR, 4), WSP(float, WS_MOD), 0);
;         else prologue_a(F, AR, 0, 5);
;     }
;     GRID_SYNC();
;     enum { T_NOP = 0, T_NORM, T_SWI, T_RES, T_STORE, T_FT, T_POST, T_SGU, T_ATTE, T_ATTO };
; #pragma unroll 1
;     for (int l = 0; l < 4; ++l) {
;         const bool even = (l & 1) == 0; const int li = l >> 1;
; #pragma unroll 1
;         for (int op = 0; op < 14; ++op) {
.LBB0_183:
	s_or_b64 exec, exec, s[4:5]
	s_add_i32 s2, 0, 0x12000
	v_writelane_b32 v255, s2, 29
	s_add_i32 s2, 0, 0x18810
	s_mov_b64 s[36:37], 0
	s_mov_b32 s21, 0
	s_mov_b32 s96, 0x3e38aa3b
	v_mov_b32_e32 v1, 0
	v_mov_b32_e32 v162, 0x358637bd
	s_mov_b32 s27, 0x800000
	s_mov_b32 s48, 0xf800000
	v_mov_b32_e32 v187, 0x260
	s_mov_b64 s[24:25], 0x80
	v_writelane_b32 v255, s2, 30
	s_movk_i32 s38, 0x1600
	v_mov_b32_e32 v193, 1
	s_barrier
	s_mov_b32 s98, 0
	s_mov_b32 s100, 0
	s_mov_b32 s99, 0
	s_nop 0
	v_writelane_b32 v255, s99, 60
	v_writelane_b32 v255, s99, 61
	v_writelane_b32 v255, s99, 62
	v_writelane_b32 v255, s99, 63
	s_mov_b32 s101, 0x880f
	s_branch .LBB0_185

; DI void attn_odd_lds(Frame& F, const float* gk  , const float* gq  , bool with_ctx) {
;     const bf16_t* P = WSP(bf16_t, WS_BIG); const bf16_t* VT = WSP(bf16_t, WS_VT); bf16_t* MIX = WSP(bf16_t, WS_H);
;     const int l16 = F.lane & 15, g = F.lane >> 4;
;     const size_t kp = LDP_O;
;     const unsigned lds0 = (unsigned)(uintptr_t)F.lds;
;     const int drow = F.wave * 8 + (F.lane & 7), dsw = (F.lane >> 3) * 8;
;     const unsigned koff = (unsigned)(drow * (int)kp + dsw) * 2u, voff = (unsigned)(drow * TT + dsw) * 2u;
;     const unsigned wofs = (unsigned)F.wave * AT_GRP;
;     const float kn = 8.0f * 1.01f * wave_max(fabsf(gk[F.lane])) * (0.125f * LOG2E);
;     const int bk = (l16 >> 3) * AT_GRP + (l16 & 7) * 16 + g * 128, bv = AT_VOFF + (l16 >> 3) * AT_GRP + (l16 & 7) * 16 + (g >> 1) * 128 + (g & 1) * 8;
;     __syncthreads();
;     for (int item = F.vcu; item < NB * 2 * 32 + (with_ctx ? NB * 2 * 2 : 0); item += F.G) {
;         const bool isc = item >= NB * 2 * 32; const int ci = item - NB * 2 * 32;
;         const int b = isc ? (ci >> 2) : (item >> 6), kvh = isc ? ((ci >> 1) & 1) : ((item >> 5) & 1);
;         const int tq = isc ? (ci & 1) * 128 : (item & 31) * 128;
;         const int qbase = (isc ? TL + b * CTXL : b * SEQ) + tq + F.wave * 16;
;         const int nlat = isc ? 0 : 64;
;         const int qrow = qbase + l16;
.LBB0_233:
	s_add_u32 s58, s60, 0x10900000
	s_addc_u32 s59, s61, 0
	s_add_u32 s62, s60, 0x19100000
	s_addc_u32 s63, s61, 0
	s_ashr_i32 s50, s79, 6
	v_writelane_b32 v255, s12, 23
	v_and_b32_e32 v194, 63, v164
	s_cmp_lt_i32 s35, 5
	s_mov_b64 s[4:5], -1
	s_cbranch_scc1 .LBB0_441
	s_cmp_lt_i32 s35, 7
	s_cbranch_scc1 .LBB0_351
	s_cmp_lt_i32 s35, 8
	s_cbranch_scc1 .LBB0_341
	s_cmp_lt_i32 s35, 9
	s_cbranch_scc1 .LBB0_271
	s_cmp_eq_u32 s35, 9
	s_cbranch_scc0 .LBB0_270
	s_mov_b32 s4, 15
	s_ashr_i32 s5, s4, 31
	s_lshl_b64 s[4:5], s[4:5], 3
	s_add_u32 s4, s0, s4
	v_readlane_b32 s6, v255, 15
	s_addc_u32 s5, s1, s5
	v_readlane_b32 s7, v255, 16
	s_load_dwordx2 s[4:5], s[4:5], 0x0
	s_lshl_b64 s[6:7], s[6:7], 2
	s_waitcnt lgkmcnt(0)
	s_add_u32 s6, s4, s6
	s_addc_u32 s7, s5, s7
	v_lshlrev_b32_e32 v0, 2, v194
	global_load_dword v2, v0, s[6:7] offset:256
	v_cmp_lt_i32_e32 vcc, v181, v180
	v_readlane_b32 s4, v255, 27
	s_cmp_ge_i32 s26, s4
	v_cndmask_b32_e32 v4, v169, v181, vcc
	v_lshlrev_b32_e32 v4, 2, v4
	v_cmp_lt_i32_e32 vcc, v182, v180
	s_barrier
	s_waitcnt vmcnt(0)
	v_and_b32_e32 v3, 0x7fffffff, v2
	ds_bpermute_b32 v3, v4, v3
	v_max_f32_e64 v2, |v2|, |v2|
	s_waitcnt lgkmcnt(0)
	v_max_f32_e32 v3, v3, v3
	v_max_f32_e32 v2, v2, v3
	v_cndmask_b32_e32 v3, v169, v182, vcc
	v_lshlrev_b32_e32 v3, 2, v3
	ds_bpermute_b32 v3, v3, v2
	v_cmp_lt_i32_e32 vcc, v183, v180
	s_waitcnt lgkmcnt(0)
	v_max_f32_e32 v3, v3, v3
	v_max_f32_e32 v2, v2, v3
	v_cndmask_b32_e32 v3, v169, v183, vcc
	v_lshlrev_b32_e32 v3, 2, v3
	ds_bpermute_b32 v3, v3, v2
	v_cmp_lt_i32_e32 vcc, v192, v180
	s_waitcnt lgkmcnt(0)
	v_max_f32_e32 v3, v3, v3
	v_max_f32_e32 v2, v2, v3
	v_cndmask_b32_e32 v3, v169, v192, vcc
	v_lshlrev_b32_e32 v3, 2, v3
	ds_bpermute_b32 v3, v3, v2
	v_cmp_lt_i32_e32 vcc, v254, v180
	s_waitcnt lgkmcnt(0)
	v_max_f32_e32 v3, v3, v3
	v_max_f32_e32 v2, v2, v3
	v_cndmask_b32_e32 v3, v169, v254, vcc
	v_lshlrev_b32_e32 v120, 2, v3
	ds_bpermute_b32 v3, v120, v2
	v_cmp_lt_i32_e32 vcc, v186, v180
	s_waitcnt lgkmcnt(0)
	v_max_f32_e32 v3, v3, v3
	v_max_f32_e32 v2, v2, v3
	v_cndmask_b32_e32 v3, v169, v186, vcc
	v_lshlrev_b32_e32 v121, 2, v3
	ds_bpermute_b32 v3, v121, v2
	s_cbranch_scc1 .LBB0_270
	s_waitcnt lgkmcnt(0)
	v_max_f32_e32 v3, v3, v3
	v_max_f32_e32 v2, v2, v3
	v_and_b32_e32 v3, 7, v164
	v_lshl_or_b32 v3, s50, 3, v3
	s_movk_i32 s4, 0x700
	v_mul_lo_u32 v5, v3, s4
	s_mov_b32 s4, 0x11000
	s_add_u32 s42, s60, 0x2c300000
	v_and_b32_e32 v4, 56, v164
	v_mul_lo_u32 v3, v3, s4
	s_mul_i32 s4, s50, 0x480
	s_addc_u32 s43, s61, 0
	v_and_b32_e32 v122, 15, v164
	v_or_b32_e32 v3, v3, v4
	v_mul_f32_e32 v2, 0x410147ae, v2
	s_add_i32 s80, s4, 0
	s_lshl_b32 s83, s50, 4
	v_lshrrev_b32_e32 v123, 4, v194
	v_or_b32_e32 v5, v5, v4
	v_lshlrev_b32_e32 v125, 1, v3
	v_mov_b32_e32 v126, v2
	v_lshlrev_b32_e32 v2, 4, v194
	v_bfe_u32 v3, v164, 3, 1
	s_add_i32 s81, s80, 0x4800
	s_add_i32 s82, s80, 0x9000
	v_or_b32_e32 v4, s83, v122
	v_and_b32_e32 v2, 0x70, v2
	v_and_b32_e32 v128, 0x80, v0
	v_lshlrev_b32_e32 v0, 3, v123
	v_mul_u32_u24_e32 v3, 0x480, v3
	s_add_u32 s8, s60, 0x400000
	v_lshlrev_b32_e32 v4, 4, v4
	v_lshlrev_b32_e32 v124, 1, v5
	v_lshlrev_b32_e32 v127, 7, v123
	v_and_b32_e32 v129, 8, v0
	s_addc_u32 s9, s61, 0
	v_and_b32_e32 v130, 0x3f0, v4
	v_add3_u32 v131, 0, v3, v2
	v_mov_b64_e32 v[102:103], s[62:63]
	v_lshlrev_b32_e32 v0, 1, v0
	s_mov_b32 s45, s26
	s_lshr_b32 s84, s26, 5
	s_lshl_b32 s84, s84, 7
	s_and_b32 s99, s26, 31
	s_or_b32 s84, s84, s99
	s_branch .LBB0_241
; DI unsigned pk2(float lo, float hi) { f32x2 v = {lo, hi}; bf16x2_t b = __builtin_convertvector(v, bf16x2_t); return __builtin_bit_cast(unsigned, b); }
; #define AT_WAIT_BAR(N) asm volatile("s_waitcnt vmcnt(" #N ") lgkmcnt(0)\n\ts_barrier" ::: "memory")
; DI void attn_store(bf16_t* op, const f32x4 (&o)[4], float ls) {
;     float l = ls; l += __shfl_xor(l, 16); l += __shfl_xor(l, 32);
;     const float inv = 1.0f / l;
; #pragma unroll
;     for (int d = 0; d < 4; ++d) { const f32x4 v = o[d] * inv; u32x2 w; w.x = pk2(v[0], v[1]); w.y = pk2(v[2], v[3]); *(u32x2*)(op + d * 16) = w; }
; }
; DI void attn_odd_lds(Frame& F, const float* gk  , const float* gq  , bool with_ctx) {
;     ...
;         AT_WAIT_BAR(0);
;         { int ln_ = F.lane; asm volatile("" : "+v"(ln_));
;           bf16_t* op = MIX + (size_t)(qbase + (ln_ & 15)) * DM + kvh * 256 + 4 * (ln_ >> 4);
; #pragma unroll
;           for (int h = 0; h < 4; ++h) attn_store(op + h * 64, o[h], ls[h]); }
;     }
.LBB0_240:
	v_mov_b32_e32 v4, v194
	s_waitcnt vmcnt(0) lgkmcnt(0)
	s_barrier
	s_lshl_b32 s20, s16, 1
	v_and_or_b32 v2, v4, 15, s85
	v_ashrrev_i32_e32 v3, 31, v2
	v_lshlrev_b64 v[2:3], 11, v[2:3]
	v_ashrrev_i32_e32 v4, 2, v4
	v_lshl_add_u64 v[2:3], s[58:59], 0, v[2:3]
	v_and_b32_e32 v4, -4, v4
	v_lshl_add_u64 v[2:3], v[2:3], 0, s[20:21]
	v_ashrrev_i32_e32 v5, 31, v4
	v_lshl_add_u64 v[2:3], v[4:5], 1, v[2:3]
	ds_bpermute_b32 v4, v120, v107
	s_and_b32 s4, s45, 31
	s_lshr_b32 s5, s45, 5
	s_lshl_b32 s5, s5, 3
	s_add_i32 s5, s5, s4
	s_addk_i32 s5, 0x400
	s_cmp_lt_u32 s4, 8
	s_cselect_b32 s5, s5, 0x800
	s_add_i32 s4, s84, 32
	s_and_b32 s99, s4, 0x60
	s_cmp_eq_u32 s99, 0
	s_cselect_b32 s4, s5, s4
	s_cmpk_lt_i32 s84, 0x400
	s_cselect_b32 s84, s4, 0x800
	s_waitcnt lgkmcnt(0)
	v_add_f32_e32 v4, v107, v4
	ds_bpermute_b32 v5, v121, v4
	s_waitcnt lgkmcnt(0)
	v_add_f32_e32 v4, v4, v5
	v_div_scale_f32 v5, s[4:5], v4, v4, 1.0
	v_rcp_f32_e32 v6, v5
	s_nop 0
	v_fma_f32 v7, -v5, v6, 1.0
	v_fmac_f32_e32 v6, v7, v6
	v_div_scale_f32 v7, vcc, 1.0, v4, 1.0
	v_mul_f32_e32 v8, v7, v6
	v_fma_f32 v9, -v5, v8, v7
	v_fmac_f32_e32 v8, v9, v6
	v_fma_f32 v5, -v5, v8, v7
	v_div_fmas_f32 v5, v5, v6, v8
	v_div_fixup_f32 v4, v5, v4, 1.0
	v_pk_mul_f32 v[6:7], v[96:97], v[4:5] op_sel_hi:[1,0]
	v_pk_mul_f32 v[8:9], v[94:95], v[4:5] op_sel_hi:[1,0]
	s_nop 0
	v_cvt_pk_bf16_f32 v8, v8, v9
	v_cvt_pk_bf16_f32 v9, v6, v7
	global_store_dwordx2 v[2:3], v[8:9], off
	v_pk_mul_f32 v[6:7], v[92:93], v[4:5] op_sel_hi:[1,0]
	v_pk_mul_f32 v[8:9], v[90:91], v[4:5] op_sel_hi:[1,0]
	s_nop 0
	v_cvt_pk_bf16_f32 v8, v8, v9
	v_cvt_pk_bf16_f32 v9, v6, v7
	global_store_dwordx2 v[2:3], v[8:9], off offset:32
	v_pk_mul_f32 v[6:7], v[88:89], v[4:5] op_sel_hi:[1,0]
	v_pk_mul_f32 v[8:9], v[86:87], v[4:5] op_sel_hi:[1,0]
	s_nop 0
	v_cvt_pk_bf16_f32 v8, v8, v9
	v_cvt_pk_bf16_f32 v9, v6, v7
	v_pk_mul_f32 v[6:7], v[84:85], v[4:5] op_sel_hi:[1,0]
	v_pk_mul_f32 v[4:5], v[82:83], v[4:5] op_sel_hi:[1,0]
	global_store_dwordx2 v[2:3], v[8:9], off offset:64
	v_cvt_pk_bf16_f32 v4, v4, v5
	v_cvt_pk_bf16_f32 v5, v6, v7
	global_store_dwordx2 v[2:3], v[4:5], off offset:96
	ds_bpermute_b32 v4, v120, v106
	s_waitcnt lgkmcnt(0)
	v_add_f32_e32 v4, v106, v4
	ds_bpermute_b32 v5, v121, v4
	s_waitcnt lgkmcnt(0)
	v_add_f32_e32 v4, v4, v5
	v_div_scale_f32 v5, s[4:5], v4, v4, 1.0
	v_rcp_f32_e32 v6, v5
	s_nop 0
	v_fma_f32 v7, -v5, v6, 1.0
	v_fmac_f32_e32 v6, v7, v6
	v_div_scale_f32 v7, vcc, 1.0, v4, 1.0
	v_mul_f32_e32 v8, v7, v6
	v_fma_f32 v9, -v5, v8, v7
	v_fmac_f32_e32 v8, v9, v6
	v_fma_f32 v5, -v5, v8, v7
	v_div_fmas_f32 v5, v5, v6, v8
	v_div_fixup_f32 v4, v5, v4, 1.0
	v_pk_mul_f32 v[6:7], v[80:81], v[4:5] op_sel_hi:[1,0]
	v_pk_mul_f32 v[8:9], v[78:79], v[4:5] op_sel_hi:[1,0]
	s_nop 0
	v_cvt_pk_bf16_f32 v8, v8, v9
	v_cvt_pk_bf16_f32 v9, v6, v7
	global_store_dwordx2 v[2:3], v[8:9], off offset:128
	v_pk_mul_f32 v[6:7], v[76:77], v[4:5] op_sel_hi:[1,0]
	v_pk_mul_f32 v[8:9], v[74:75], v[4:5] op_sel_hi:[1,0]
	s_nop 0
	v_cvt_pk_bf16_f32 v8, v8, v9
	v_cvt_pk_bf16_f32 v9, v6, v7
	global_store_dwordx2 v[2:3], v[8:9], off offset:160
	v_pk_mul_f32 v[6:7], v[72:73], v[4:5] op_sel_hi:[1,0]
	v_pk_mul_f32 v[8:9], v[70:71], v[4:5] op_sel_hi:[1,0]
	s_nop 0
	v_cvt_pk_bf16_f32 v8, v8, v9
	v_cvt_pk_bf16_f32 v9, v6, v7
	v_pk_mul_f32 v[6:7], v[68:69], v[4:5] op_sel_hi:[1,0]
	v_pk_mul_f32 v[4:5], v[66:67], v[4:5] op_sel_hi:[1,0]
	global_store_dwordx2 v[2:3], v[8:9], off offset:192
	v_cvt_pk_bf16_f32 v4, v4, v5
	v_cvt_pk_bf16_f32 v5, v6, v7
	global_store_dwordx2 v[2:3], v[4:5], off offset:224
	ds_bpermute_b32 v4, v120, v105
	s_waitcnt lgkmcnt(0)
	v_add_f32_e32 v4, v105, v4
	ds_bpermute_b32 v5, v121, v4
	s_waitcnt lgkmcnt(0)
	v_add_f32_e32 v4, v4, v5
	v_div_scale_f32 v5, s[4:5], v4, v4, 1.0
	v_rcp_f32_e32 v6, v5
	s_nop 0
	v_fma_f32 v7, -v5, v6, 1.0
	v_fmac_f32_e32 v6, v7, v6
	v_div_scale_f32 v7, vcc, 1.0, v4, 1.0
	v_mul_f32_e32 v8, v7, v6
	v_fma_f32 v9, -v5, v8, v7
	v_fmac_f32_e32 v8, v9, v6
	v_fma_f32 v5, -v5, v8, v7
	v_div_fmas_f32 v5, v5, v6, v8
	v_div_fixup_f32 v4, v5, v4, 1.0
	v_pk_mul_f32 v[6:7], v[64:65], v[4:5] op_sel_hi:[1,0]
	v_pk_mul_f32 v[8:9], v[62:63], v[4:5] op_sel_hi:[1,0]
	s_nop 0
	v_cvt_pk_bf16_f32 v8, v8, v9
	v_cvt_pk_bf16_f32 v9, v6, v7
	global_store_dwordx2 v[2:3], v[8:9], off offset:256
	v_pk_mul_f32 v[6:7], v[60:61], v[4:5] op_sel_hi:[1,0]
	v_pk_mul_f32 v[8:9], v[58:59], v[4:5] op_sel_hi:[1,0]
	s_nop 0
	v_cvt_pk_bf16_f32 v8, v8, v9
	v_cvt_pk_bf16_f32 v9, v6, v7
	global_store_dwordx2 v[2:3], v[8:9], off offset:288
	v_pk_mul_f32 v[6:7], v[56:57], v[4:5] op_sel_hi:[1,0]
	v_pk_mul_f32 v[8:9], v[54:55], v[4:5] op_sel_hi:[1,0]
	s_nop 0
	v_cvt_pk_bf16_f32 v8, v8, v9
	v_cvt_pk_bf16_f32 v9, v6, v7
	v_pk_mul_f32 v[6:7], v[52:53], v[4:5] op_sel_hi:[1,0]
	v_pk_mul_f32 v[4:5], v[50:51], v[4:5] op_sel_hi:[1,0]
	global_store_dwordx2 v[2:3], v[8:9], off offset:320
	v_cvt_pk_bf16_f32 v4, v4, v5
	v_cvt_pk_bf16_f32 v5, v6, v7
	global_store_dwordx2 v[2:3], v[4:5], off offset:352
	ds_bpermute_b32 v4, v120, v104
	s_waitcnt lgkmcnt(0)
	v_add_f32_e32 v4, v104, v4
	ds_bpermute_b32 v5, v121, v4
	s_waitcnt lgkmcnt(0)
	v_add_f32_e32 v4, v4, v5
	v_div_scale_f32 v5, s[4:5], v4, v4, 1.0
	v_rcp_f32_e32 v6, v5
	v_readlane_b32 s4, v255, 27
	s_cmp_ge_i32 s84, s4
	v_fma_f32 v7, -v5, v6, 1.0
	v_fmac_f32_e32 v6, v7, v6
	v_div_scale_f32 v7, vcc, 1.0, v4, 1.0
	v_mul_f32_e32 v8, v7, v6
	v_fma_f32 v9, -v5, v8, v7
	v_fmac_f32_e32 v8, v9, v6
	v_fma_f32 v5, -v5, v8, v7
	v_div_fmas_f32 v5, v5, v6, v8
	v_div_fixup_f32 v4, v5, v4, 1.0
	v_pk_mul_f32 v[6:7], v[40:41], v[4:5] op_sel_hi:[1,0]
	v_pk_mul_f32 v[8:9], v[38:39], v[4:5] op_sel_hi:[1,0]
	s_nop 0
	v_cvt_pk_bf16_f32 v8, v8, v9
	v_cvt_pk_bf16_f32 v9, v6, v7
	global_store_dwordx2 v[2:3], v[8:9], off offset:384
	v_pk_mul_f32 v[6:7], v[36:37], v[4:5] op_sel_hi:[1,0]
	v_pk_mul_f32 v[8:9], v[34:35], v[4:5] op_sel_hi:[1,0]
	s_nop 0
	v_cvt_pk_bf16_f32 v8, v8, v9
	v_cvt_pk_bf16_f32 v9, v6, v7
	global_store_dwordx2 v[2:3], v[8:9], off offset:416
	v_pk_mul_f32 v[6:7], v[32:33], v[4:5] op_sel_hi:[1,0]
	v_pk_mul_f32 v[8:9], v[30:31], v[4:5] op_sel_hi:[1,0]
	s_nop 0
	v_cvt_pk_bf16_f32 v8, v8, v9
	v_cvt_pk_bf16_f32 v9, v6, v7
	v_pk_mul_f32 v[6:7], v[28:29], v[4:5] op_sel_hi:[1,0]
	v_pk_mul_f32 v[4:5], v[26:27], v[4:5] op_sel_hi:[1,0]
	global_store_dwordx2 v[2:3], v[8:9], off offset:448
	v_cvt_pk_bf16_f32 v4, v4, v5
	v_cvt_pk_bf16_f32 v5, v6, v7
	global_store_dwordx2 v[2:3], v[4:5], off offset:480
	s_cbranch_scc1 .LBB0_269

; #define LAS __attribute__((address_space(3)))
; DI void attn_even_lds(Frame& F, const float* rpb  , const float* gk  , const float* gq  ) {
;     ...
;     const size_t kp = LDP_E;
;     const unsigned lds0 = (unsigned)(uintptr_t)F.lds;
;     LAS float* blall = (LAS float*)(F.lds + 4 * AT_SLOT);
;     const int drow = F.wave * 8 + (F.lane & 7), dsw = (F.lane >> 3) * 8;
;     const unsigned koff = (unsigned)(drow * (int)kp + dsw) * 2u, voff = (unsigned)(drow * TT + dsw) * 2u;
;     const unsigned wofs = (unsigned)F.wave * AT_GRP;
;     const float kn = 8.0f * 1.01f * wave_max(fabsf(gk[F.lane])) * (0.125f * LOG2E);
;     const int bk = (l16 >> 3) * AT_GRP + (l16 & 7) * 16 + g * 128, bv = AT_VOFF + (l16 >> 3) * AT_GRP + (l16 & 7) * 16 + (g >> 1) * 128 + (g & 1) * 8;
;     LAS u32x4* dct = (LAS u32x4*)(F.lds + 4 * AT_SLOT + 22528);
;     float bmx = 0.f;
;     for (int i = F.tid; i < 12 * 465; i += 512) { const float bv_ = rpb[i] * LOG2E; blall[i] = bv_; bmx = fmaxf(bmx, fabsf(bv_)); }
;     LAS float* wm = (LAS float*)(F.lds + 4 * AT_SLOT + 22528 + 4096);
;     bmx = wave_max(bmx); if (F.lane == 0) wm[F.wave] = bmx;
;     if (F.wave == 0) {
; #pragma unroll
;         for (int j = 0; j < 4; ++j) {
;             const int qc = 16 * j + l16, kcol0 = j == 0 ? 0 : (j == 1 ? 8 : (j == 2 ? 24 : 32)), cs = qc < 8 ? 0 : (qc > 56 ? 48 : qc - 8);
;             unsigned a = 0u, bb = 0u, vm = 0u;
; #pragma unroll
;             for (int e = 0; e < 8; ++e) { const int kc = kcol0 + (e < 4 ? 4 * g + e : 16 + 4 * g + (e - 4));
;                 if (kc >= cs && kc < cs + 16) vm |= 1u << e;
;                 int d = kc - qc + 15; d = d < 0 ? 0 : (d > 30 ? 30 : d);
;                 if (e < 4) a |= (unsigned)d << (8 * e); else bb |= (unsigned)d << (8 * (e - 4)); }
;             dct[j * 64 + F.lane] = (u32x4){a, bb, vm, 0u};
;         }
;     }
;     __syncthreads();
;     const float bmax = fmaxf(fmaxf(fmaxf(wm[0], wm[1]), fmaxf(wm[2], wm[3])), fmaxf(fmaxf(wm[4], wm[5]), fmaxf(wm[6], wm[7])));
;     for (int item = F.vcu; item < NB * 12 * 8; item += F.G) {
;         const int b = item / 96, rem = item % 96, h = rem >> 3, rg = rem & 7, r = rg * 8 + F.wave;
;         const int r0 = r < 4 ? 0 : (r > 60 ? 56 : r - 4);
;         const int rlo = rg == 0 ? 0 : rg * 8 - 4, rhi = (rg == 7 ? 56 : rg * 8 + 3) + 7;
;         const int nloc = rhi - rlo + 1, n = nloc + 4;
.LBB0_280:
	v_and_b32_e32 v2, 7, v164
	v_lshl_or_b32 v2, s50, 3, v2
	s_movk_i32 s4, 0x600
	v_mul_lo_u32 v6, v2, s4
	s_mov_b32 s4, 0x11000
	s_waitcnt lgkmcnt(0)
	v_and_b32_e32 v3, 56, v164
	v_mul_lo_u32 v2, v2, s4
	v_or_b32_e32 v2, v2, v3
	v_lshlrev_b32_e32 v199, 1, v2
	v_lshrrev_b32_e32 v2, 3, v165
	v_or_b32_e32 v6, v6, v3
	v_mul_u32_u24_e32 v204, 0x480, v2
	v_lshlrev_b32_e32 v2, 4, v194
	v_lshlrev_b32_e32 v168, 3, v197
	v_lshlrev_b32_e32 v198, 1, v6
	s_mul_i32 s42, s50, 0x480
	v_and_b32_e32 v205, 0x70, v2
	v_lshlrev_b32_e32 v206, 7, v197
	v_and_b32_e32 v207, 0x80, v0
	v_and_b32_e32 v208, 8, v168
	s_lshr_b32 s85, s33, 5
	s_mul_i32 s85, s85, 0xc0
	s_and_b32 s99, s33, 31
	s_add_i32 s85, s85, s99
	s_cmpk_gt_i32 s33, 0x5ff
	s_barrier
	s_cbranch_scc1 .LBB0_321
	s_add_i32 s4, 0, 0x18800
	v_mov_b32_e32 v0, s4
	ds_read_b128 v[6:9], v0
	v_readlane_b32 s4, v255, 30
	s_add_u32 s43, s60, 0x2c300000
	s_addc_u32 s80, s61, 0
	s_add_i32 s81, s42, 0
	s_waitcnt lgkmcnt(0)
	v_max_f32_e32 v0, v7, v7
	v_max_f32_e32 v3, v6, v6
	v_max_f32_e32 v0, v3, v0
	v_max_f32_e32 v3, v9, v9
	v_max_f32_e32 v6, v8, v8
	v_max_f32_e32 v3, v6, v3
	v_mov_b32_e32 v6, s4
	ds_read_b128 v[6:9], v6
	s_add_i32 s4, 0, 0x17800
	s_add_i32 s82, s81, 0x4800
	s_add_i32 s83, s81, 0x9000
	v_add3_u32 v214, 0, v204, v205
	s_waitcnt lgkmcnt(0)
	v_max_f32_e32 v9, v9, v9
	v_max_f32_e32 v8, v8, v8
	v_max_f32_e32 v8, v8, v9
	v_max3_f32 v6, v6, v7, v8
	v_max3_f32 v209, v0, v3, v6
	v_max_f32_e32 v0, v5, v5
	v_max_f32_e32 v3, v4, v4
	v_max_f32_e32 v0, v3, v0
	v_mul_f32_e32 v0, 0x410147ae, v0
	v_mul_f32_e32 v210, 0x3e38aa3b, v0
	v_lshlrev_b32_e32 v0, 1, v168
	v_lshl_add_u64 v[170:171], s[62:63], 0, v[0:1]
	v_add_u32_e32 v0, s4, v2
	s_add_i32 s4, 0, 0x17c00
	v_add_u32_e32 v211, s4, v2
	s_add_i32 s4, 0, 0x18000
	v_add_u32_e32 v212, s4, v2
	s_add_i32 s4, 0, 0x18400
	v_add_u32_e32 v213, s4, v2
	s_sub_i32 s84, 0, s50
	s_branch .LBB0_283
; DI unsigned pk2(float lo, float hi) { f32x2 v = {lo, hi}; bf16x2_t b = __builtin_convertvector(v, bf16x2_t); return __builtin_bit_cast(unsigned, b); }
; #define AT_WAIT_BAR(N) asm volatile("s_waitcnt vmcnt(" #N ") lgkmcnt(0)\n\ts_barrier" ::: "memory")
; DI void attn_store(bf16_t* op, const f32x4 (&o)[4], float ls) {
;     float l = ls; l += __shfl_xor(l, 16); l += __shfl_xor(l, 32);
;     const float inv = 1.0f / l;
; #pragma unroll
;     for (int d = 0; d < 4; ++d) { const f32x4 v = o[d] * inv; u32x2 w; w.x = pk2(v[0], v[1]); w.y = pk2(v[2], v[3]); *(u32x2*)(op + d * 16) = w; }
; }
; DI void attn_even_lds(Frame& F, const float* rpb  , const float* gk  , const float* gq  ) {
;     ...
;         AT_WAIT_BAR(0);
;         { int ln_ = F.lane; asm volatile("" : "+v"(ln_));
;           bf16_t* op = MIX + (size_t)(b * SEQ + r * 64 + (ln_ & 15)) * DM + h * 64 + 4 * (ln_ >> 4);
; #pragma unroll
;           for (int j = 0; j < 4; ++j) attn_store(op + (size_t)(16 * j) * DM, o[j], ls[j]); }
.LBB0_282:
	v_mov_b32_e32 v4, v194
	s_waitcnt vmcnt(0) lgkmcnt(0)
	s_barrier
	s_add_i32 s85, s85, 32
	s_lshr_b32 s99, s33, 5
	s_mul_i32 s99, s99, 0xc0
	s_addk_i32 s99, 0xc0
	s_cmp_ge_i32 s85, s99
	s_cselect_b32 s85, 0x1000, s85
	v_and_or_b32 v2, v4, 15, s86
	v_ashrrev_i32_e32 v3, 31, v2
	v_lshlrev_b64 v[2:3], 11, v[2:3]
	v_ashrrev_i32_e32 v4, 2, v4
	v_lshl_add_u64 v[2:3], s[58:59], 0, v[2:3]
	v_and_b32_e32 v4, -4, v4
	v_lshl_add_u64 v[2:3], s[6:7], 1, v[2:3]
	v_ashrrev_i32_e32 v5, 31, v4
	v_lshl_add_u64 v[2:3], v[4:5], 1, v[2:3]
	ds_bpermute_b32 v4, v195, v177
	s_cmpk_gt_i32 s85, 0x5ff
	s_waitcnt lgkmcnt(0)
	v_add_f32_e32 v4, v177, v4
	ds_bpermute_b32 v5, v196, v4
	s_waitcnt lgkmcnt(0)
	v_add_f32_e32 v4, v4, v5
	v_div_scale_f32 v5, s[4:5], v4, v4, 1.0
	v_rcp_f32_e32 v6, v5
	s_nop 0
	v_fma_f32 v7, -v5, v6, 1.0
	v_fmac_f32_e32 v6, v7, v6
	v_div_scale_f32 v7, vcc, 1.0, v4, 1.0
	v_mul_f32_e32 v8, v7, v6
	v_fma_f32 v9, -v5, v8, v7
	v_fmac_f32_e32 v8, v9, v6
	v_fma_f32 v5, -v5, v8, v7
	v_div_fmas_f32 v5, v5, v6, v8
	v_div_fixup_f32 v4, v5, v4, 1.0
	v_pk_mul_f32 v[6:7], v[88:89], v[4:5] op_sel_hi:[1,0]
	v_pk_mul_f32 v[8:9], v[86:87], v[4:5] op_sel_hi:[1,0]
	s_nop 0
	v_cvt_pk_bf16_f32 v8, v8, v9
	v_cvt_pk_bf16_f32 v9, v6, v7
	global_store_dwordx2 v[2:3], v[8:9], off
	v_pk_mul_f32 v[6:7], v[96:97], v[4:5] op_sel_hi:[1,0]
	v_pk_mul_f32 v[8:9], v[94:95], v[4:5] op_sel_hi:[1,0]
	s_nop 0
	v_cvt_pk_bf16_f32 v8, v8, v9
	v_cvt_pk_bf16_f32 v9, v6, v7
	global_store_dwordx2 v[2:3], v[8:9], off offset:32
	v_pk_mul_f32 v[6:7], v[104:105], v[4:5] op_sel_hi:[1,0]
	v_pk_mul_f32 v[8:9], v[102:103], v[4:5] op_sel_hi:[1,0]
	s_nop 0
	v_cvt_pk_bf16_f32 v8, v8, v9
	v_cvt_pk_bf16_f32 v9, v6, v7
	v_pk_mul_f32 v[6:7], v[112:113], v[4:5] op_sel_hi:[1,0]
	v_pk_mul_f32 v[4:5], v[110:111], v[4:5] op_sel_hi:[1,0]
	global_store_dwordx2 v[2:3], v[8:9], off offset:64
	v_cvt_pk_bf16_f32 v4, v4, v5
	v_cvt_pk_bf16_f32 v5, v6, v7
	global_store_dwordx2 v[2:3], v[4:5], off offset:96
	ds_bpermute_b32 v4, v195, v176
	s_waitcnt lgkmcnt(0)
	v_add_f32_e32 v4, v176, v4
	ds_bpermute_b32 v5, v196, v4
	s_waitcnt lgkmcnt(0)
	v_add_f32_e32 v4, v4, v5
	v_div_scale_f32 v5, s[4:5], v4, v4, 1.0
	v_rcp_f32_e32 v6, v5
	s_mov_b32 s4, 0x8000
	v_fma_f32 v7, -v5, v6, 1.0
	v_fmac_f32_e32 v6, v7, v6
	v_div_scale_f32 v7, vcc, 1.0, v4, 1.0
	v_mul_f32_e32 v8, v7, v6
	v_fma_f32 v9, -v5, v8, v7
	v_fmac_f32_e32 v8, v9, v6
	v_fma_f32 v5, -v5, v8, v7
	v_div_fmas_f32 v5, v5, v6, v8
	v_div_fixup_f32 v4, v5, v4, 1.0
	v_pk_mul_f32 v[6:7], v[116:117], v[4:5] op_sel_hi:[1,0]
	v_pk_mul_f32 v[8:9], v[114:115], v[4:5] op_sel_hi:[1,0]
	v_pk_mul_f32 v[10:11], v[118:119], v[4:5] op_sel_hi:[1,0]
	v_cvt_pk_bf16_f32 v8, v8, v9
	v_cvt_pk_bf16_f32 v9, v6, v7
	v_add_co_u32_e32 v6, vcc, s4, v2
	v_cvt_pk_bf16_f32 v10, v10, v11
	s_nop 0
	v_addc_co_u32_e32 v7, vcc, 0, v3, vcc
	global_store_dwordx2 v[6:7], v[8:9], off
	v_pk_mul_f32 v[8:9], v[120:121], v[4:5] op_sel_hi:[1,0]
	s_nop 0
	v_cvt_pk_bf16_f32 v11, v8, v9
	global_store_dwordx2 v[6:7], v[10:11], off offset:32
	v_pk_mul_f32 v[8:9], v[124:125], v[4:5] op_sel_hi:[1,0]
	v_pk_mul_f32 v[10:11], v[122:123], v[4:5] op_sel_hi:[1,0]
	s_nop 0
	v_cvt_pk_bf16_f32 v10, v10, v11
	v_cvt_pk_bf16_f32 v11, v8, v9
	v_pk_mul_f32 v[8:9], v[128:129], v[4:5] op_sel_hi:[1,0]
	v_pk_mul_f32 v[4:5], v[126:127], v[4:5] op_sel_hi:[1,0]
	global_store_dwordx2 v[6:7], v[10:11], off offset:64
	v_cvt_pk_bf16_f32 v4, v4, v5
	v_cvt_pk_bf16_f32 v5, v8, v9
	global_store_dwordx2 v[6:7], v[4:5], off offset:96
	ds_bpermute_b32 v4, v195, v179
	s_waitcnt lgkmcnt(0)
	v_add_f32_e32 v4, v179, v4
	ds_bpermute_b32 v5, v196, v4
	s_waitcnt lgkmcnt(0)
	v_add_f32_e32 v4, v4, v5
	v_div_scale_f32 v5, s[4:5], v4, v4, 1.0
	v_rcp_f32_e32 v6, v5
	s_mov_b32 s4, 0x10000
	v_fma_f32 v7, -v5, v6, 1.0
	v_fmac_f32_e32 v6, v7, v6
	v_div_scale_f32 v7, vcc, 1.0, v4, 1.0
	v_mul_f32_e32 v8, v7, v6
	v_fma_f32 v9, -v5, v8, v7
	v_fmac_f32_e32 v8, v9, v6
	v_fma_f32 v5, -v5, v8, v7
	v_div_fmas_f32 v5, v5, v6, v8
	v_div_fixup_f32 v4, v5, v4, 1.0
	v_pk_mul_f32 v[6:7], v[132:133], v[4:5] op_sel_hi:[1,0]
	v_pk_mul_f32 v[8:9], v[130:131], v[4:5] op_sel_hi:[1,0]
	v_pk_mul_f32 v[10:11], v[134:135], v[4:5] op_sel_hi:[1,0]
	v_cvt_pk_bf16_f32 v8, v8, v9
	v_cvt_pk_bf16_f32 v9, v6, v7
	v_add_co_u32_e32 v6, vcc, s4, v2
	v_cvt_pk_bf16_f32 v10, v10, v11
	s_nop 0
	v_addc_co_u32_e32 v7, vcc, 0, v3, vcc
	global_store_dwordx2 v[6:7], v[8:9], off
	v_pk_mul_f32 v[8:9], v[136:137], v[4:5] op_sel_hi:[1,0]
	s_nop 0
	v_cvt_pk_bf16_f32 v11, v8, v9
	global_store_dwordx2 v[6:7], v[10:11], off offset:32
	v_pk_mul_f32 v[8:9], v[140:141], v[4:5] op_sel_hi:[1,0]
	v_pk_mul_f32 v[10:11], v[138:139], v[4:5] op_sel_hi:[1,0]
	s_nop 0
	v_cvt_pk_bf16_f32 v10, v10, v11
	v_cvt_pk_bf16_f32 v11, v8, v9
	v_pk_mul_f32 v[8:9], v[144:145], v[4:5] op_sel_hi:[1,0]
	v_pk_mul_f32 v[4:5], v[142:143], v[4:5] op_sel_hi:[1,0]
	global_store_dwordx2 v[6:7], v[10:11], off offset:64
	v_cvt_pk_bf16_f32 v4, v4, v5
	v_cvt_pk_bf16_f32 v5, v8, v9
	global_store_dwordx2 v[6:7], v[4:5], off offset:96
	ds_bpermute_b32 v4, v195, v178
	s_waitcnt lgkmcnt(0)
	v_add_f32_e32 v4, v178, v4
	ds_bpermute_b32 v5, v196, v4
	s_waitcnt lgkmcnt(0)
	v_add_f32_e32 v4, v4, v5
	v_div_scale_f32 v5, s[4:5], v4, v4, 1.0
	v_rcp_f32_e32 v6, v5
	s_mov_b32 s4, 0x18000
	v_fma_f32 v7, -v5, v6, 1.0
	v_fmac_f32_e32 v6, v7, v6
	v_div_scale_f32 v7, vcc, 1.0, v4, 1.0
	v_mul_f32_e32 v8, v7, v6
	v_fma_f32 v9, -v5, v8, v7
	v_fmac_f32_e32 v8, v9, v6
	v_fma_f32 v5, -v5, v8, v7
	v_div_fmas_f32 v5, v5, v6, v8
	v_div_fixup_f32 v4, v5, v4, 1.0
	v_pk_mul_f32 v[6:7], v[148:149], v[4:5] op_sel_hi:[1,0]
	v_pk_mul_f32 v[8:9], v[146:147], v[4:5] op_sel_hi:[1,0]
	v_add_co_u32_e32 v2, vcc, s4, v2
	v_cvt_pk_bf16_f32 v8, v8, v9
	v_cvt_pk_bf16_f32 v9, v6, v7
	v_addc_co_u32_e32 v3, vcc, 0, v3, vcc
	global_store_dwordx2 v[2:3], v[8:9], off
	v_pk_mul_f32 v[6:7], v[152:153], v[4:5] op_sel_hi:[1,0]
	v_pk_mul_f32 v[8:9], v[150:151], v[4:5] op_sel_hi:[1,0]
	s_nop 0
	v_cvt_pk_bf16_f32 v8, v8, v9
	v_cvt_pk_bf16_f32 v9, v6, v7
	global_store_dwordx2 v[2:3], v[8:9], off offset:32
	v_pk_mul_f32 v[6:7], v[156:157], v[4:5] op_sel_hi:[1,0]
	v_pk_mul_f32 v[8:9], v[154:155], v[4:5] op_sel_hi:[1,0]
	s_nop 0
	v_cvt_pk_bf16_f32 v8, v8, v9
	v_cvt_pk_bf16_f32 v9, v6, v7
	v_pk_mul_f32 v[6:7], v[160:161], v[4:5] op_sel_hi:[1,0]
	v_pk_mul_f32 v[4:5], v[158:159], v[4:5] op_sel_hi:[1,0]
	global_store_dwordx2 v[2:3], v[8:9], off offset:64
	v_cvt_pk_bf16_f32 v4, v4, v5
	v_cvt_pk_bf16_f32 v5, v6, v7
	global_store_dwordx2 v[2:3], v[4:5], off offset:96
	s_cbranch_scc1 .LBB0_320

; DI void attn_evenctx_lds(Frame& F, const float* gk  , const float* gq  ) {
;     ...
;     const unsigned lds0 = (unsigned)(uintptr_t)F.lds;
;     const int drow = F.wave * 8 + (F.lane & 7), dsw = (F.lane >> 3) * 8;
;     const unsigned koff = (unsigned)(drow * (int)kp + dsw) * 2u, voff = (unsigned)(drow * TT + dsw) * 2u;
;     const unsigned wofs = (unsigned)F.wave * AT_GRP;
;     const float kn = 8.0f * 1.01f * wave_max(fabsf(gk[F.lane])) * (0.125f * LOG2E);
;     const int bk = (l16 >> 3) * AT_GRP + (l16 & 7) * 16 + g * 128, bv = AT_VOFF + (l16 >> 3) * AT_GRP + (l16 & 7) * 16 + (g >> 1) * 128 + (g & 1) * 8;
;     __syncthreads();
;     for (int item = F.vcu; item < NB * 12; item += F.G) {
;         const int b = item / 12, h = item % 12;
;         const bool act = F.wave < 4;
;         const int qbase = TL + b * CTXL + (F.wave & 3) * 64;
;         const int nlat = 0;
;         const int qrow = qbase + l16;
.LBB0_321:
	global_load_dword v0, v[166:167], off offset:256
	s_and_b32 s99, s33, 31
	s_lshr_b32 s85, s33, 5
	s_mul_i32 s85, s85, 24
	s_add_i32 s85, s85, s99
	s_cmp_lt_u32 s99, 24
	s_cselect_b32 s85, s85, 0x1000
	s_cmpk_gt_i32 s85, 0xbf
	s_barrier
	s_waitcnt vmcnt(0)
	v_and_b32_e32 v2, 0x7fffffff, v0
	ds_bpermute_b32 v2, v200, v2
	v_max_f32_e64 v0, |v0|, |v0|
	s_waitcnt lgkmcnt(0)
	v_max_f32_e32 v2, v2, v2
	v_max_f32_e32 v0, v0, v2
	ds_bpermute_b32 v2, v201, v0
	s_waitcnt lgkmcnt(0)
	v_max_f32_e32 v2, v2, v2
	v_max_f32_e32 v0, v0, v2
	ds_bpermute_b32 v2, v202, v0
	s_waitcnt lgkmcnt(0)
	v_max_f32_e32 v2, v2, v2
	v_max_f32_e32 v0, v0, v2
	ds_bpermute_b32 v2, v203, v0
	s_waitcnt lgkmcnt(0)
	v_max_f32_e32 v2, v2, v2
	v_max_f32_e32 v0, v0, v2
	ds_bpermute_b32 v2, v195, v0
	s_waitcnt lgkmcnt(0)
	v_max_f32_e32 v2, v2, v2
	v_max_f32_e32 v0, v0, v2
	ds_bpermute_b32 v2, v196, v0
	s_cbranch_scc1 .LBB0_340
	s_waitcnt lgkmcnt(0)
	v_max_f32_e32 v2, v2, v2
	s_add_i32 s10, s42, 0
	v_max_f32_e32 v0, v0, v2
	s_add_i32 s11, s10, 0x4800
	s_add_i32 s16, s10, 0x9000
	s_add_i32 s17, s10, 0xd800
	s_and_b32 s18, s79, 0xc0
	v_mul_f32_e32 v0, 0x410147ae, v0
	s_cmp_lt_i32 s50, 4
	v_mul_f32_e32 v112, 0x3e38aa3b, v0
	s_cselect_b64 s[68:69], -1, 0
	v_add3_u32 v0, v204, v207, v205
	s_add_i32 s4, 0, 0x2400
	v_add3_u32 v113, v0, v208, s4
	v_add_u32_e32 v0, v204, v206
	v_add3_u32 v114, v0, v205, 0
	v_lshlrev_b32_e32 v0, 1, v168
	s_mov_b32 s19, s85
	s_branch .LBB0_324
.LBB0_323:
	s_movk_i32 s19, 0x1000
	s_cmpk_gt_i32 s19, 0xbf
	s_cbranch_scc1 .LBB0_340

; DI void grid_barrier(unsigned* cnt, unsigned target) {
;     asm volatile("s_waitcnt vmcnt(0) lgkmcnt(0)" ::: "memory");
;     __syncthreads();
;     if (threadIdx.x == 0) {
;         __builtin_amdgcn_fence(__ATOMIC_RELEASE, "agent");
;         asm volatile("s_waitcnt vmcnt(0)" ::: "memory");
;         __hip_atomic_fetch_add(cnt, 1u, __ATOMIC_RELAXED, __HIP_MEMORY_SCOPE_AGENT);
;         while (__hip_atomic_load(cnt, __ATOMIC_RELAXED, __HIP_MEMORY_SCOPE_AGENT) < target) __builtin_amdgcn_s_sleep(2);
;         __builtin_amdgcn_fence(__ATOMIC_ACQUIRE, "agent");
;         asm volatile("s_waitcnt vmcnt(0)" ::: "memory");
;     }
;     __syncthreads();
; }
.Lwd_D:
	s_mov_b64 exec, s[30:31]
	s_barrier
	s_cmp_eq_u32 s44, 10
	s_cbranch_scc0 .Lres_nowd
	v_readlane_b32 s33, v255, 63
	s_lshl_b32 s33, s33, 8
	s_mov_b64 s[30:31], exec
	v_readlane_b32 s40, v255, 3
	v_readlane_b32 s41, v255, 4
	s_and_b64 s[40:41], s[30:31], s[40:41]
	s_mov_b64 exec, s[40:41]
	s_cbranch_execz .Lwd_E
.Lwp_E:
	global_load_dword v0, v1, s[14:15] offset:200 sc1
	s_waitcnt vmcnt(0)
	v_cmp_gt_u32_e32 vcc, s33, v0
	s_cbranch_vccz .Lwi_E
	s_sleep 2
	s_branch .Lwp_E

; DI void grid_barrier(unsigned* cnt, unsigned target) {
;     asm volatile("s_waitcnt vmcnt(0) lgkmcnt(0)" ::: "memory");
;     __syncthreads();
;     if (threadIdx.x == 0) {
;         __builtin_amdgcn_fence(__ATOMIC_RELEASE, "agent");
;         asm volatile("s_waitcnt vmcnt(0)" ::: "memory");
;         __hip_atomic_fetch_add(cnt, 1u, __ATOMIC_RELAXED, __HIP_MEMORY_SCOPE_AGENT);
;         while (__hip_atomic_load(cnt, __ATOMIC_RELAXED, __HIP_MEMORY_SCOPE_AGENT) < target) __builtin_amdgcn_s_sleep(2);
;         __builtin_amdgcn_fence(__ATOMIC_ACQUIRE, "agent");
;         asm volatile("s_waitcnt vmcnt(0)" ::: "memory");
;     }
;     __syncthreads();
; }
.Lxl_pre:
	s_waitcnt lgkmcnt(0)
	s_cmp_eq_u32 s13, 0x100
	s_cbranch_scc0 .Lxl_no
	s_cmp_eq_u32 s44, 9
	s_cbranch_scc0 .Lat_not9
	s_waitcnt vmcnt(0) lgkmcnt(0)
	s_barrier
	v_readlane_b32 s10, v255, 63
	s_add_u32 s10, s10, 1
	s_nop 0
	v_writelane_b32 v255, s10, 63
	s_mov_b64 s[4:5], exec
	v_readlane_b32 s6, v255, 3
	v_readlane_b32 s7, v255, 4
	s_and_b64 s[6:7], s[4:5], s[6:7]
	s_mov_b64 exec, s[6:7]
	s_cbranch_execz .Lar_E
	buffer_wbl2 sc1
	s_waitcnt vmcnt(0)
	v_mov_b32_e32 v0, 1
	global_atomic_add v1, v0, s[14:15] offset:200

; DI void grid_barrier(unsigned* cnt, unsigned target) {
;     asm volatile("s_waitcnt vmcnt(0) lgkmcnt(0)" ::: "memory");
;     __syncthreads();
;     if (threadIdx.x == 0) {
;         __builtin_amdgcn_fence(__ATOMIC_RELEASE, "agent");
;         asm volatile("s_waitcnt vmcnt(0)" ::: "memory");
;         __hip_atomic_fetch_add(cnt, 1u, __ATOMIC_RELAXED, __HIP_MEMORY_SCOPE_AGENT);
;         while (__hip_atomic_load(cnt, __ATOMIC_RELAXED, __HIP_MEMORY_SCOPE_AGENT) < target) __builtin_amdgcn_s_sleep(2);
;         __builtin_amdgcn_fence(__ATOMIC_ACQUIRE, "agent");
;         asm volatile("s_waitcnt vmcnt(0)" ::: "memory");
;     }
;     __syncthreads();
; }
.Llb_A:
	s_mov_b64 exec, s[4:5]
	s_barrier
	s_branch .LBB0_585
.Lat_not9:
	s_cmp_eq_u32 s44, 2
	s_cbranch_scc0 .Lxl_not2
	s_branch .Lxl_yes
